# barriers 3 and 4 also replaced by row-block counters (no grid-wide barrier after the prepass one), on top of the transposes unroll and row prefetch
# baseline (speedup 1.0000x reference)
.Lqb3_cn:
	s_add_i32 s3, s3, 0x80
	s_sub_i32 s10, s10, 1
	s_cmp_lg_u32 s10, 0
	s_cbranch_scc1 .Lqb3_cw
	s_bfe_u32 s11, s2, 0x10002
	s_lshl_b32 s11, s11, 3
	s_add_i32 s11, s11, 16
	s_bfe_u32 s14, s2, 0x30004
	s_mov_b32 s10, 8
.Lqb3_lw:
	s_and_b32 s3, s14, 7
	s_add_i32 s3, s3, s11
	s_lshl_b32 s3, s3, 7
	s_add_i32 s3, s3, 0x70
	v_mov_b32_e32 v1, s3
	s_mov_b32 s15, 0

.Lqb3_ln:
	s_add_i32 s14, s14, 1
	s_sub_i32 s10, s10, 1
	s_cmp_lg_u32 s10, 0
	s_cbranch_scc1 .Lqb3_lw
	s_waitcnt vmcnt(0)

.LBB0_396:
	s_waitcnt vmcnt(0)
	s_waitcnt lgkmcnt(0)
	s_barrier
	s_mov_b64 s[4:5], exec
	v_readlane_b32 s0, v219, 25
	v_readlane_b32 s1, v219, 26
	s_and_b64 s[0:1], s[4:5], s[0:1]
	s_mov_b64 exec, s[0:1]
	s_cbranch_execz .LBB0_448
	v_readlane_b32 s0, v219, 27
	v_readlane_b32 s1, v219, 28
	v_readlane_b32 s2, v219, 30
	s_waitcnt vmcnt(0) lgkmcnt(0)
	buffer_inv sc1
	s_bfe_u32 s3, s2, 0x10002
	s_lshl_b32 s3, s3, 3
	s_bfe_u32 s10, s2, 0x30004
	s_add_i32 s3, s3, s10
	s_add_i32 s3, s3, 16
	s_lshl_b32 s3, s3, 7
	s_add_i32 s3, s3, 0x60
	s_lshr_b32 s10, s2, 4
	s_lshl_b32 s10, s10, 7
	s_add_i32 s10, s10, 0x60
	s_and_b32 s11, s2, 31
	s_lshl_b32 s11, s11, 7
	s_add_i32 s11, s11, 0x60
	v_mov_b32_e32 v0, 1
	v_mov_b32_e32 v1, s3
	v_mov_b32_e32 v2, s10
	s_nop 1
	global_atomic_add v1, v0, s[0:1]
	global_atomic_add v2, v0, s[0:1]
	v_mov_b32_e32 v2, 0x1180
	s_nop 1
	global_atomic_add v2, v0, s[0:1]
	s_cmp_ge_u32 s2, 64
	s_cbranch_scc1 .Lfb4_not
	v_mov_b32_e32 v2, 0x11c0
	s_nop 1
	global_atomic_add v2, v0, s[0:1]
.Lfb4_not:
	v_mov_b32_e32 v1, s11
	s_mov_b32 s15, 0

.Lfb4_done:
	v_mov_b32_e32 v1, 0x11c0
	s_mov_b32 s15, 0
.Lfb4_tspin:
	global_load_dword v2, v1, s[0:1] sc1
	s_waitcnt vmcnt(0)
	v_readfirstlane_b32 s13, v2
	s_nop 1
	s_cmp_ge_u32 s13, 64
	s_cbranch_scc1 .Lfb4_tdone
	s_sleep 4
	s_add_i32 s15, s15, 1
	s_cmp_lt_u32 s15, 0x200000
	s_cbranch_scc1 .Lfb4_tspin

.Lgb6_done:
	v_mov_b32_e32 v1, 0x1180
	s_mov_b32 s15, 0

.LBB0_1120:
	s_waitcnt vmcnt(0)
	s_barrier
	s_mov_b64 s[6:7], exec
	v_readlane_b32 s0, v219, 25
	v_readlane_b32 s1, v219, 26
	s_and_b64 s[0:1], s[6:7], s[0:1]
	s_mov_b64 exec, s[0:1]
	s_cbranch_execz .LBB0_1172
	v_readlane_b32 s0, v219, 27
	v_readlane_b32 s1, v219, 28
	v_readlane_b32 s2, v219, 30
	s_waitcnt vmcnt(0) lgkmcnt(0)
	buffer_inv sc1
	s_bfe_u32 s3, s2, 0x10002
	s_lshl_b32 s3, s3, 3
	s_bfe_u32 s10, s2, 0x30004
	s_add_i32 s3, s3, s10
	s_add_i32 s3, s3, 16
	s_lshl_b32 s3, s3, 7
	s_add_i32 s3, s3, 0x60
	s_lshr_b32 s10, s2, 4
	s_lshl_b32 s10, s10, 7
	s_add_i32 s10, s10, 0x60
	s_and_b32 s11, s2, 31
	s_lshl_b32 s11, s11, 7
	s_add_i32 s11, s11, 0x60
	v_mov_b32_e32 v0, 1
	v_mov_b32_e32 v1, s3
	v_mov_b32_e32 v2, s10
	s_nop 1
	global_atomic_add v1, v0, s[0:1]
	global_atomic_add v2, v0, s[0:1]
	v_mov_b32_e32 v2, 0x1140
	s_nop 1
	global_atomic_add v2, v0, s[0:1]
	v_mov_b32_e32 v1, s11
	s_mov_b32 s15, 0
.Lfb11_spin:
	global_load_dword v2, v1, s[0:1] sc1
	s_waitcnt vmcnt(0)
	v_readfirstlane_b32 s13, v2
	s_nop 1
	s_cmp_ge_u32 s13, 32
	s_cbranch_scc1 .Lfb11_done
	s_sleep 1
	s_add_i32 s15, s15, 1
	s_cmp_lt_u32 s15, 0x200000
	s_cbranch_scc1 .Lfb11_spin
